# b_w_out f32->bf16 conversion moved from the layer-0 out-projection tail to the layer-1 in-projection tail
# speedup vs baseline: 1.0038x; 1.0038x over previous
.LBB0_154:
	v_readlane_b32 s0, v249, 25
	v_readlane_b32 s1, v249, 26
	s_and_b64 vcc, exec, s[0:1]
	s_cbranch_vccz .LBB0_212
	v_mov_b32_e32 v14, v182
	v_readlane_b32 s1, v249, 28
	v_readfirstlane_b32 s0, v14
	s_ashr_i32 s0, s0, 6
	s_add_i32 s6, s1, s0
	s_addk_i32 s6, 0xf800
	s_cmp_gt_i32 s6, 0xa5ff
	s_cbranch_scc1 .LBB0_212
	v_lshlrev_b32_e32 v0, 3, v14
	s_mul_i32 s1, s0, 0x2100
	v_bfe_u32 v33, v14, 3, 3
	v_and_b32_e32 v0, 56, v0
	s_add_i32 s4, s1, 0
	v_bfe_u32 v32, v14, 5, 1
	v_mul_u32_u24_e32 v1, 0x84, v0
	s_waitcnt lgkmcnt(1)
	v_lshlrev_b32_e32 v2, 2, v33
	v_lshlrev_b32_e32 v144, 1, v0
	v_add3_u32 v34, s4, v1, v2
	v_lshl_add_u64 v[0:1], s[22:23], 0, v[144:145]
	s_mov_b64 s[4:5], 0x6400000
	v_mul_u32_u24_e32 v15, 0x84, v32
	s_waitcnt lgkmcnt(0)
	v_lshl_add_u64 v[2:3], v[0:1], 0, s[4:5]
	s_mov_b64 s[4:5], 0x3000000
	v_or_b32_e32 v15, s1, v15
	v_readlane_b32 s1, v249, 53
	v_lshl_add_u64 v[4:5], v[0:1], 0, s[4:5]
	s_mov_b64 s[4:5], 0x9000000
	s_add_i32 s8, s1, s0
	s_addk_i32 s8, 0xf800
	v_readlane_b32 s1, v249, 54
	v_lshl_add_u64 v[8:9], v[0:1], 0, s[4:5]
	s_mov_b64 s[4:5], 0x3800000
	v_lshlrev_b32_e32 v14, 2, v14
	s_add_i32 s9, s1, s0
	s_addk_i32 s9, 0xf800
	v_readlane_b32 s1, v249, 55
	v_lshl_add_u64 v[10:11], v[0:1], 0, s[4:5]
	s_mov_b64 s[4:5], 0x1800000
	v_and_b32_e32 v14, 0x7c, v14
	s_add_i32 s10, s1, s0
	s_addk_i32 s10, 0xf800
	v_readlane_b32 s1, v249, 56
	v_or_b32_e32 v35, 8, v33
	v_or_b32_e32 v36, 16, v33
	v_or_b32_e32 v37, 24, v33
	v_lshl_add_u64 v[6:7], s[12:13], 0, v[144:145]
	v_lshl_add_u64 v[12:13], v[0:1], 0, s[4:5]
	v_add3_u32 v38, v15, v14, 0
	v_mov_b32_e32 v15, v145
	v_or_b32_e32 v39, 14, v32
	v_or_b32_e32 v40, 12, v32
	v_or_b32_e32 v41, 10, v32
	v_or_b32_e32 v42, 8, v32
	v_or_b32_e32 v43, 6, v32
	v_or_b32_e32 v44, 4, v32
	v_or_b32_e32 v45, 2, v32
	s_lshl_b32 s7, s6, 5
	s_add_i32 s11, s1, s0
	s_addk_i32 s11, 0xf800
	s_branch .LBB0_158

.LBB0_810:
	v_readlane_b32 s10, v248, 10
	s_and_b64 s[4:5], s[24:25], exec
	s_movk_i32 s8, 0x7200
	v_readlane_b32 s11, v248, 11
	s_cselect_b32 s6, 0x4c00, s8
	s_and_b64 s[4:5], s[10:11], exec
	s_cselect_b32 s4, s6, 0xa600
	s_and_b64 s[6:7], s[24:25], exec
	s_mov_b32 s6, 0xbc00
	s_cselect_b32 s5, s8, 0x7200
	s_cselect_b32 s8, s6, 0xa600
	s_and_b64 s[6:7], s[10:11], exec
	s_cselect_b32 s8, s5, s8
	s_cmp_lt_u32 s4, s8
	v_readlane_b32 s10, v249, 50
	s_cselect_b64 s[6:7], -1, 0
	v_readlane_b32 s11, v249, 51
	s_and_b64 s[6:7], s[10:11], s[6:7]
	s_andn2_b64 vcc, exec, s[6:7]
	s_movk_i32 s53, 0x1000
	s_cbranch_vccnz .LBB0_874
	v_mov_b32_e32 v16, v182
	v_readlane_b32 s6, v248, 0
	v_readfirstlane_b32 s5, v16
	s_ashr_i32 s5, s5, 6
	s_add_i32 s6, s6, s4
	s_add_i32 s9, s6, s5
	s_cmp_ge_i32 s9, s8
	s_cbranch_scc1 .LBB0_874
	v_lshlrev_b32_e32 v0, 3, v16
	v_and_b32_e32 v0, 56, v0
	v_lshlrev_b32_e32 v144, 1, v0
	s_mul_i32 s10, s5, 0x2100
	v_bfe_u32 v35, v16, 3, 3
	v_mul_u32_u24_e32 v4, 0x84, v0
	v_lshl_add_u64 v[0:1], s[26:27], 0, v[144:145]
	s_mov_b64 s[6:7], 0xa600000
	s_add_i32 s11, s10, 0
	v_lshl_add_u64 v[2:3], v[0:1], 0, s[6:7]
	v_lshlrev_b32_e32 v5, 2, v35
	s_mov_b64 s[6:7], 0x6400000
	v_add3_u32 v36, s11, v4, v5
	v_lshl_add_u64 v[4:5], v[0:1], 0, s[6:7]
	s_mov_b64 s[6:7], 0x3000000
	v_lshl_add_u64 v[6:7], v[0:1], 0, s[6:7]
	s_mov_b64 s[6:7], 0x2000000
	v_lshl_add_u64 v[8:9], v[0:1], 0, s[6:7]
	s_mov_b64 s[6:7], 0x9000000
	v_lshl_add_u64 v[10:11], v[0:1], 0, s[6:7]
	s_mov_b64 s[6:7], 0x3800000
	v_lshl_add_u64 v[12:13], v[0:1], 0, s[6:7]
	s_mov_b64 s[6:7], 0x1800000
	v_lshl_add_u64 v[14:15], v[0:1], 0, s[6:7]
	v_readlane_b32 s6, v249, 61
	s_add_i32 s6, s6, s4
	s_add_i32 s11, s6, s5
	v_readlane_b32 s6, v249, 62
	s_add_i32 s6, s6, s4
	s_add_i32 s16, s6, s5
	v_readlane_b32 s6, v249, 63
	v_bfe_u32 v34, v16, 5, 1
	s_add_i32 s6, s6, s4
	v_mul_u32_u24_e32 v17, 0x84, v34
	v_lshlrev_b32_e32 v16, 2, v16
	s_add_i32 s17, s6, s5
	v_readlane_b32 s6, v248, 1
	v_or_b32_e32 v17, s10, v17
	v_and_b32_e32 v16, 0x7c, v16
	s_add_i32 s4, s6, s4
	v_or_b32_e32 v37, 8, v35
	v_or_b32_e32 v38, 16, v35
	v_or_b32_e32 v39, 24, v35
	v_add3_u32 v40, v17, v16, 0
	v_mov_b32_e32 v17, v145
	v_or_b32_e32 v41, 0xffff5a0e, v34
	s_lshl_b32 s10, s9, 5
	v_or_b32_e32 v42, 0xffff5a0c, v34
	v_or_b32_e32 v43, 0xffff5a0a, v34
	v_or_b32_e32 v44, 0xffff5a08, v34
	v_or_b32_e32 v45, 0xffff5a06, v34
	v_or_b32_e32 v46, 0xffff5a04, v34
	v_or_b32_e32 v47, 0xffff5a02, v34
	v_or_b32_e32 v48, 0xffff5a00, v34
	v_or_b32_e32 v49, 14, v34
	v_or_b32_e32 v50, 12, v34
	v_or_b32_e32 v51, 10, v34
	v_or_b32_e32 v52, 8, v34
	v_or_b32_e32 v53, 6, v34
	v_or_b32_e32 v54, 4, v34
	v_or_b32_e32 v55, 2, v34
	s_add_i32 s18, s4, s5
	s_branch .LBB0_814
